# attention loop: the four K/V LDS-DMA stage loads issued one at a time between different PV MFMAs instead of as one burst
# baseline (speedup 1.0000x reference)
.Latt_stgA_skip1:
	ds_read_b128 v[90:93], v131 offset:50176
	s_waitcnt lgkmcnt(4)
	v_mfma_f32_16x16x32_bf16 v[46:49], v[176:179], v[14:17], v[46:49]
	ds_read_b128 v[176:179], v131 offset:58368
	s_cmp_ge_u32 s73, s71
	s_cbranch_scc1 .Latt_stgA_skip2
	v_lshl_add_u64 v[192:193], v[114:115], 0, s[44:45]
	s_add_i32 m0, s49, 0x2000
	s_nop 0
	global_load_lds_dwordx4 v[192:193], off
.Latt_stgA_skip2:
	v_exp_f32_e32 v98, v70
	v_exp_f32_e32 v99, v71
	v_exp_f32_e32 v100, v72
	v_exp_f32_e32 v101, v73
	ds_read_b128 v[180:183], v131 offset:52224
	s_waitcnt lgkmcnt(4)
	v_mfma_f32_16x16x32_bf16 v[38:41], v[82:85], v[14:17], v[38:41]
	v_max3_f32 v194, v168, v169, v170
	v_max3_f32 v194, v194, v171, v172
	v_max3_f32 v194, v194, v173, v174
	v_max3_f32 v194, v194, v175, v195
	v_mfma_f32_16x16x32_bf16 v[2:5], v[154:157], v[14:17], v[2:5]
	v_exp_f32_e32 v102, v22
	v_exp_f32_e32 v103, v23
	v_exp_f32_e32 v104, v24
	v_exp_f32_e32 v105, v25
	ds_read_b128 v[94:97], v131 offset:60416
	s_waitcnt lgkmcnt(3)
	v_mfma_f32_16x16x32_bf16 v[30:33], v[90:93], v[6:9], v[30:33]
	ds_read_b128 v[90:93], v131 offset:62464
	s_cmp_ge_u32 s73, s71
	s_cbranch_scc1 .Latt_stgA_skip3
	s_mov_b32 m0, s50
	s_nop 0
	global_load_lds_dwordx4 v[118:119], off
.Latt_stgA_skip3:
	v_mov_b32_e32 v158, v194
	s_nop 1
	v_permlane16_swap_b32_e32 v194, v158
	v_max_f32_e32 v194, v194, v158
	s_waitcnt lgkmcnt(2)
	v_mfma_f32_16x16x32_bf16 v[50:53], v[180:183], v[6:9], v[50:53]
	ds_read_b128 v[180:183], v131 offset:64512
	s_cmp_ge_u32 s73, s71
	s_cbranch_scc1 .Latt_stgA_skip4
	s_add_i32 m0, s51, 0xe000
	s_nop 0
	global_load_lds_dwordx4 v[116:117], off
.Latt_stgA_skip4:
	v_exp_f32_e32 v133, v26
	v_exp_f32_e32 v134, v27
	v_exp_f32_e32 v135, v28
	v_exp_f32_e32 v136, v29
	v_mfma_f32_16x16x32_bf16 v[42:45], v[78:81], v[6:9], v[42:45]
	v_mov_b32_e32 v158, v194
	s_nop 1
	v_permlane32_swap_b32_e32 v194, v158
	v_max_f32_e32 v194, v194, v158
	v_mfma_f32_16x16x32_bf16 v[34:37], v[86:89], v[6:9], v[34:37]
	v_cvt_pk_bf16_f32 v14, v145, v146
	v_cvt_pk_bf16_f32 v15, v147, v148
	v_cvt_pk_bf16_f32 v16, v98, v99
	v_cvt_pk_bf16_f32 v17, v100, v101
	v_cvt_pk_bf16_f32 v184, v102, v103
	v_cvt_pk_bf16_f32 v185, v104, v105
	v_cvt_pk_bf16_f32 v186, v133, v134
	v_cvt_pk_bf16_f32 v187, v135, v136
	v_mfma_f32_16x16x32_bf16 v[58:61], v[176:179], v[6:9], v[58:61]
	s_waitcnt lgkmcnt(2)
	v_mfma_f32_16x16x32_bf16 v[54:57], v[94:97], v[6:9], v[54:57]
	s_waitcnt lgkmcnt(1)
	v_mfma_f32_16x16x32_bf16 v[46:49], v[90:93], v[6:9], v[46:49]
	s_waitcnt lgkmcnt(0)
	v_mfma_f32_16x16x32_bf16 v[38:41], v[180:183], v[6:9], v[38:41]
	v_mfma_f32_16x16x32_bf16 v[2:5], v[154:157], v[6:9], v[2:5]
	s_andn2_b64 vcc, exec, s[34:35]
	s_cbranch_vccnz .LBB0_1331
	v_sub_f32_e32 v160, v160, v132
	v_sub_f32_e32 v161, v161, v132
	v_sub_f32_e32 v162, v162, v132
	v_sub_f32_e32 v163, v163, v132
	v_sub_f32_e32 v164, v164, v132
	v_sub_f32_e32 v165, v165, v132
	v_sub_f32_e32 v166, v166, v132
	v_sub_f32_e32 v167, v167, v132
	v_sub_f32_e32 v168, v168, v132
	v_sub_f32_e32 v169, v169, v132
	v_sub_f32_e32 v170, v170, v132
	v_sub_f32_e32 v171, v171, v132
	v_sub_f32_e32 v172, v172, v132
	v_sub_f32_e32 v173, v173, v132
	v_sub_f32_e32 v174, v174, v132
	v_sub_f32_e32 v175, v175, v132
	v_sub_f32_e32 v194, v194, v132
	v_pk_mul_f32 v[40:41], v[0:1], v[40:41] op_sel_hi:[0,1]
	v_pk_mul_f32 v[48:49], v[0:1], v[48:49] op_sel_hi:[0,1]
	v_pk_mul_f32 v[56:57], v[0:1], v[56:57] op_sel_hi:[0,1]
	v_pk_mul_f32 v[60:61], v[0:1], v[60:61] op_sel_hi:[0,1]
	v_pk_mul_f32 v[36:37], v[0:1], v[36:37] op_sel_hi:[0,1]
	v_pk_mul_f32 v[44:45], v[0:1], v[44:45] op_sel_hi:[0,1]
	v_pk_mul_f32 v[52:53], v[0:1], v[52:53] op_sel_hi:[0,1]
	v_pk_mul_f32 v[32:33], v[0:1], v[32:33] op_sel_hi:[0,1]
	v_pk_mul_f32 v[38:39], v[0:1], v[38:39] op_sel_hi:[0,1]
	v_pk_mul_f32 v[46:47], v[0:1], v[46:47] op_sel_hi:[0,1]
	v_pk_mul_f32 v[54:55], v[0:1], v[54:55] op_sel_hi:[0,1]
	v_pk_mul_f32 v[58:59], v[0:1], v[58:59] op_sel_hi:[0,1]
	v_pk_mul_f32 v[34:35], v[0:1], v[34:35] op_sel_hi:[0,1]
	v_pk_mul_f32 v[42:43], v[0:1], v[42:43] op_sel_hi:[0,1]
	v_pk_mul_f32 v[50:51], v[0:1], v[50:51] op_sel_hi:[0,1]
	v_pk_mul_f32 v[30:31], v[0:1], v[30:31] op_sel_hi:[0,1]
	v_pk_mul_f32 v[4:5], v[0:1], v[4:5] op_sel_hi:[0,1]
	v_pk_mul_f32 v[2:3], v[0:1], v[2:3] op_sel_hi:[0,1]

.Latt_stgB_skip2:
	v_exp_f32_e32 v98, v164
	v_exp_f32_e32 v99, v165
	v_exp_f32_e32 v100, v166
	v_exp_f32_e32 v101, v167
	ds_read_b128 v[180:183], v131 offset:52224
	s_waitcnt lgkmcnt(4)
	v_mfma_f32_16x16x32_bf16 v[38:41], v[82:85], v[14:17], v[38:41]
	v_max3_f32 v194, v22, v23, v24
	v_max3_f32 v194, v194, v25, v26
	v_max3_f32 v194, v194, v27, v28
	v_max3_f32 v194, v194, v29, v195
	v_mfma_f32_16x16x32_bf16 v[2:5], v[154:157], v[14:17], v[2:5]
	v_exp_f32_e32 v102, v168
	v_exp_f32_e32 v103, v169
	v_exp_f32_e32 v104, v170
	v_exp_f32_e32 v105, v171
	ds_read_b128 v[94:97], v131 offset:60416
	s_waitcnt lgkmcnt(3)
	v_mfma_f32_16x16x32_bf16 v[30:33], v[90:93], v[184:187], v[30:33]
	ds_read_b128 v[90:93], v131 offset:62464
	s_cmp_ge_u32 s73, s71
	s_cbranch_scc1 .Latt_stgB_skip3
	s_mov_b32 m0, s50
	s_nop 0
	global_load_lds_dwordx4 v[118:119], off
.Latt_stgB_skip3:
	v_mov_b32_e32 v158, v194
	s_nop 1
	v_permlane16_swap_b32_e32 v194, v158
	v_max_f32_e32 v194, v194, v158
	s_waitcnt lgkmcnt(2)
	v_mfma_f32_16x16x32_bf16 v[50:53], v[180:183], v[184:187], v[50:53]
	ds_read_b128 v[180:183], v131 offset:64512
	s_cmp_ge_u32 s73, s71
	s_cbranch_scc1 .Latt_stgB_skip4
	s_add_i32 m0, s51, 0xe000
	s_nop 0
	global_load_lds_dwordx4 v[116:117], off
.Latt_stgB_skip4:
	v_exp_f32_e32 v133, v172
	v_exp_f32_e32 v134, v173
	v_exp_f32_e32 v135, v174
	v_exp_f32_e32 v136, v175
	v_mfma_f32_16x16x32_bf16 v[42:45], v[78:81], v[184:187], v[42:45]
	v_mov_b32_e32 v158, v194
	s_nop 1
	v_permlane32_swap_b32_e32 v194, v158
	v_max_f32_e32 v194, v194, v158
	v_mfma_f32_16x16x32_bf16 v[34:37], v[86:89], v[184:187], v[34:37]
	v_cvt_pk_bf16_f32 v14, v145, v146
	v_cvt_pk_bf16_f32 v15, v147, v148
	v_cvt_pk_bf16_f32 v16, v98, v99
	v_cvt_pk_bf16_f32 v17, v100, v101
	v_cvt_pk_bf16_f32 v6, v102, v103
	v_cvt_pk_bf16_f32 v7, v104, v105
	v_cvt_pk_bf16_f32 v8, v133, v134
	v_cvt_pk_bf16_f32 v9, v135, v136
	v_mfma_f32_16x16x32_bf16 v[58:61], v[176:179], v[184:187], v[58:61]
	s_waitcnt lgkmcnt(2)
	v_mfma_f32_16x16x32_bf16 v[54:57], v[94:97], v[184:187], v[54:57]
	s_waitcnt lgkmcnt(1)
	v_mfma_f32_16x16x32_bf16 v[46:49], v[90:93], v[184:187], v[46:49]
	s_waitcnt lgkmcnt(0)
	v_mfma_f32_16x16x32_bf16 v[38:41], v[180:183], v[184:187], v[38:41]
	v_mfma_f32_16x16x32_bf16 v[2:5], v[154:157], v[184:187], v[2:5]
	s_andn2_b64 vcc, exec, s[34:35]
	s_cbranch_vccnz .Latt_B_1331
	v_sub_f32_e32 v74, v74, v132
	v_sub_f32_e32 v75, v75, v132
	v_sub_f32_e32 v76, v76, v132
	v_sub_f32_e32 v77, v77, v132
	v_sub_f32_e32 v70, v70, v132
	v_sub_f32_e32 v71, v71, v132
	v_sub_f32_e32 v72, v72, v132
	v_sub_f32_e32 v73, v73, v132
	v_sub_f32_e32 v22, v22, v132
	v_sub_f32_e32 v23, v23, v132
	v_sub_f32_e32 v24, v24, v132
	v_sub_f32_e32 v25, v25, v132
	v_sub_f32_e32 v26, v26, v132
	v_sub_f32_e32 v27, v27, v132
	v_sub_f32_e32 v28, v28, v132
	v_sub_f32_e32 v29, v29, v132
	v_sub_f32_e32 v194, v194, v132
	v_pk_mul_f32 v[40:41], v[0:1], v[40:41] op_sel_hi:[0,1]
	v_pk_mul_f32 v[48:49], v[0:1], v[48:49] op_sel_hi:[0,1]
	v_pk_mul_f32 v[56:57], v[0:1], v[56:57] op_sel_hi:[0,1]
	v_pk_mul_f32 v[60:61], v[0:1], v[60:61] op_sel_hi:[0,1]
	v_pk_mul_f32 v[36:37], v[0:1], v[36:37] op_sel_hi:[0,1]
	v_pk_mul_f32 v[44:45], v[0:1], v[44:45] op_sel_hi:[0,1]
	v_pk_mul_f32 v[52:53], v[0:1], v[52:53] op_sel_hi:[0,1]
	v_pk_mul_f32 v[32:33], v[0:1], v[32:33] op_sel_hi:[0,1]
	v_pk_mul_f32 v[38:39], v[0:1], v[38:39] op_sel_hi:[0,1]
	v_pk_mul_f32 v[46:47], v[0:1], v[46:47] op_sel_hi:[0,1]
	v_pk_mul_f32 v[54:55], v[0:1], v[54:55] op_sel_hi:[0,1]
	v_pk_mul_f32 v[58:59], v[0:1], v[58:59] op_sel_hi:[0,1]
	v_pk_mul_f32 v[34:35], v[0:1], v[34:35] op_sel_hi:[0,1]
	v_pk_mul_f32 v[42:43], v[0:1], v[42:43] op_sel_hi:[0,1]
	v_pk_mul_f32 v[50:51], v[0:1], v[50:51] op_sel_hi:[0,1]
	v_pk_mul_f32 v[30:31], v[0:1], v[30:31] op_sel_hi:[0,1]
	v_pk_mul_f32 v[4:5], v[0:1], v[4:5] op_sel_hi:[0,1]
	v_pk_mul_f32 v[2:3], v[0:1], v[2:3] op_sel_hi:[0,1]
